# modulate-norm phases store H with 16-byte stores (neighbour lanes exchange their halves)
# baseline (speedup 1.0000x reference)
.LBB0_618:
	v_lshrrev_b32_e32 v210, 5, v176
	v_lshlrev_b32_e32 v210, 4, v210
	v_and_b32_e32 v211, 16, v176
	v_lshlrev_b32_e32 v211, 5, v211
	v_or_b32_e32 v210, v210, v211
	v_writelane_b32 v255, s83, 10
	v_writelane_b32 v255, s82, 11
	v_writelane_b32 v255, s85, 12
	v_writelane_b32 v255, s84, 13
	v_readfirstlane_b32 s8, v32
	v_readfirstlane_b32 s9, v33
	v_readfirstlane_b32 s10, v34
	v_readfirstlane_b32 s11, v35
	s_cmp_lg_u64 s[6:7], 0
	s_cselect_b32 s12, 1, 0
	s_mov_b32 s13, 0
	v_writelane_b32 v255, s8, 14
	v_writelane_b32 v255, s9, 15
	v_writelane_b32 v255, s10, 16
	v_writelane_b32 v255, s11, 17
	v_writelane_b32 v255, s12, 18
	v_writelane_b32 v255, s13, 19
	v_readfirstlane_b32 s10, v38
	v_readfirstlane_b32 s11, v39
	s_add_u32 s10, s10, 0x1000
	s_addc_u32 s11, s11, 0
	global_load_dwordx4 v[178:181], v176, s[10:11] offset:-4096
	global_load_dwordx4 v[182:185], v176, s[10:11] offset:-3072
	global_load_dwordx4 v[186:189], v176, s[10:11] offset:-2048
	global_load_dwordx4 v[190:193], v176, s[10:11] offset:-1024
	global_load_dwordx4 v[194:197], v176, s[10:11] offset:0
	global_load_dwordx4 v[198:201], v176, s[10:11] offset:1024
	global_load_dwordx4 v[202:205], v176, s[10:11] offset:2048
	global_load_dwordx4 v[206:209], v176, s[10:11] offset:3072
	s_sub_i32 s3, s2, s88

.Lnrm_p1_wd:
	s_mov_b32 vcc_lo, 0xaaaaaaaa
	s_mov_b32 vcc_hi, 0xaaaaaaaa
	v_pk_mul_f32 v[0:1], v[178:179], v[0:1]
	v_pk_add_f32 v[172:173], v[128:129], 1.0 op_sel_hi:[1,0]
	v_pk_fma_f32 v[0:1], v[172:173], v[0:1], v[96:97]
	v_pk_mul_f32 v[2:3], v[180:181], v[2:3]
	v_pk_add_f32 v[174:175], v[130:131], 1.0 op_sel_hi:[1,0]
	v_pk_fma_f32 v[2:3], v[174:175], v[2:3], v[98:99]
	v_cvt_pk_bf16_f32 v168, v0, v1
	v_cvt_pk_bf16_f32 v169, v2, v3
	v_pk_mul_f32 v[4:5], v[182:183], v[4:5]
	v_pk_add_f32 v[172:173], v[132:133], 1.0 op_sel_hi:[1,0]
	v_pk_fma_f32 v[4:5], v[172:173], v[4:5], v[100:101]
	v_pk_mul_f32 v[6:7], v[184:185], v[6:7]
	v_pk_add_f32 v[174:175], v[134:135], 1.0 op_sel_hi:[1,0]
	v_pk_fma_f32 v[6:7], v[174:175], v[6:7], v[102:103]
	v_cvt_pk_bf16_f32 v170, v4, v5
	v_cvt_pk_bf16_f32 v171, v6, v7
	s_nop 1
	v_mov_b32_dpp v220, v168 quad_perm:[1,0,3,2] row_mask:0xf bank_mask:0xf
	v_mov_b32_dpp v221, v169 quad_perm:[1,0,3,2] row_mask:0xf bank_mask:0xf
	v_mov_b32_dpp v222, v170 quad_perm:[1,0,3,2] row_mask:0xf bank_mask:0xf
	v_mov_b32_dpp v223, v171 quad_perm:[1,0,3,2] row_mask:0xf bank_mask:0xf
	v_cndmask_b32_e32 v160, v168, v222, vcc
	v_cndmask_b32_e32 v161, v169, v223, vcc
	v_cndmask_b32_e32 v162, v220, v170, vcc
	v_cndmask_b32_e32 v163, v221, v171, vcc
	global_store_dwordx4 v210, v[160:163], s[8:9] offset:0
	s_nop 1
	v_pk_mul_f32 v[8:9], v[186:187], v[8:9]
	v_pk_add_f32 v[172:173], v[136:137], 1.0 op_sel_hi:[1,0]
	v_pk_fma_f32 v[8:9], v[172:173], v[8:9], v[104:105]
	v_pk_mul_f32 v[10:11], v[188:189], v[10:11]
	v_pk_add_f32 v[174:175], v[138:139], 1.0 op_sel_hi:[1,0]
	v_pk_fma_f32 v[10:11], v[174:175], v[10:11], v[106:107]
	v_cvt_pk_bf16_f32 v168, v8, v9
	v_cvt_pk_bf16_f32 v169, v10, v11
	v_pk_mul_f32 v[12:13], v[190:191], v[12:13]
	v_pk_add_f32 v[172:173], v[140:141], 1.0 op_sel_hi:[1,0]
	v_pk_fma_f32 v[12:13], v[172:173], v[12:13], v[108:109]
	v_pk_mul_f32 v[14:15], v[192:193], v[14:15]
	v_pk_add_f32 v[174:175], v[142:143], 1.0 op_sel_hi:[1,0]
	v_pk_fma_f32 v[14:15], v[174:175], v[14:15], v[110:111]
	v_cvt_pk_bf16_f32 v170, v12, v13
	v_cvt_pk_bf16_f32 v171, v14, v15
	s_nop 1
	v_mov_b32_dpp v220, v168 quad_perm:[1,0,3,2] row_mask:0xf bank_mask:0xf
	v_mov_b32_dpp v221, v169 quad_perm:[1,0,3,2] row_mask:0xf bank_mask:0xf
	v_mov_b32_dpp v222, v170 quad_perm:[1,0,3,2] row_mask:0xf bank_mask:0xf
	v_mov_b32_dpp v223, v171 quad_perm:[1,0,3,2] row_mask:0xf bank_mask:0xf
	v_cndmask_b32_e32 v160, v168, v222, vcc
	v_cndmask_b32_e32 v161, v169, v223, vcc
	v_cndmask_b32_e32 v162, v220, v170, vcc
	v_cndmask_b32_e32 v163, v221, v171, vcc
	global_store_dwordx4 v210, v[160:163], s[8:9] offset:1024
	s_nop 1
	v_pk_mul_f32 v[16:17], v[194:195], v[16:17]
	v_pk_add_f32 v[172:173], v[144:145], 1.0 op_sel_hi:[1,0]
	v_pk_fma_f32 v[16:17], v[172:173], v[16:17], v[112:113]
	v_pk_mul_f32 v[18:19], v[196:197], v[18:19]
	v_pk_add_f32 v[174:175], v[146:147], 1.0 op_sel_hi:[1,0]
	v_pk_fma_f32 v[18:19], v[174:175], v[18:19], v[114:115]
	v_cvt_pk_bf16_f32 v168, v16, v17
	v_cvt_pk_bf16_f32 v169, v18, v19
	v_pk_mul_f32 v[20:21], v[198:199], v[20:21]
	v_pk_add_f32 v[172:173], v[148:149], 1.0 op_sel_hi:[1,0]
	v_pk_fma_f32 v[20:21], v[172:173], v[20:21], v[116:117]
	v_pk_mul_f32 v[22:23], v[200:201], v[22:23]
	v_pk_add_f32 v[174:175], v[150:151], 1.0 op_sel_hi:[1,0]
	v_pk_fma_f32 v[22:23], v[174:175], v[22:23], v[118:119]
	v_cvt_pk_bf16_f32 v170, v20, v21
	v_cvt_pk_bf16_f32 v171, v22, v23
	s_nop 1
	v_mov_b32_dpp v220, v168 quad_perm:[1,0,3,2] row_mask:0xf bank_mask:0xf
	v_mov_b32_dpp v221, v169 quad_perm:[1,0,3,2] row_mask:0xf bank_mask:0xf
	v_mov_b32_dpp v222, v170 quad_perm:[1,0,3,2] row_mask:0xf bank_mask:0xf
	v_mov_b32_dpp v223, v171 quad_perm:[1,0,3,2] row_mask:0xf bank_mask:0xf
	v_cndmask_b32_e32 v160, v168, v222, vcc
	v_cndmask_b32_e32 v161, v169, v223, vcc
	v_cndmask_b32_e32 v162, v220, v170, vcc
	v_cndmask_b32_e32 v163, v221, v171, vcc
	global_store_dwordx4 v210, v[160:163], s[8:9] offset:2048
	s_nop 1
	v_pk_mul_f32 v[24:25], v[202:203], v[24:25]
	v_pk_add_f32 v[172:173], v[152:153], 1.0 op_sel_hi:[1,0]
	v_pk_fma_f32 v[24:25], v[172:173], v[24:25], v[120:121]
	v_pk_mul_f32 v[26:27], v[204:205], v[26:27]
	v_pk_add_f32 v[174:175], v[154:155], 1.0 op_sel_hi:[1,0]
	v_pk_fma_f32 v[26:27], v[174:175], v[26:27], v[122:123]
	v_cvt_pk_bf16_f32 v168, v24, v25
	v_cvt_pk_bf16_f32 v169, v26, v27
	v_pk_mul_f32 v[28:29], v[206:207], v[28:29]
	v_pk_add_f32 v[172:173], v[156:157], 1.0 op_sel_hi:[1,0]
	v_pk_fma_f32 v[28:29], v[172:173], v[28:29], v[124:125]
	v_pk_mul_f32 v[30:31], v[208:209], v[30:31]
	v_pk_add_f32 v[174:175], v[158:159], 1.0 op_sel_hi:[1,0]
	v_pk_fma_f32 v[30:31], v[174:175], v[30:31], v[126:127]
	v_cvt_pk_bf16_f32 v170, v28, v29
	v_cvt_pk_bf16_f32 v171, v30, v31
	s_nop 1
	v_mov_b32_dpp v220, v168 quad_perm:[1,0,3,2] row_mask:0xf bank_mask:0xf
	v_mov_b32_dpp v221, v169 quad_perm:[1,0,3,2] row_mask:0xf bank_mask:0xf
	v_mov_b32_dpp v222, v170 quad_perm:[1,0,3,2] row_mask:0xf bank_mask:0xf
	v_mov_b32_dpp v223, v171 quad_perm:[1,0,3,2] row_mask:0xf bank_mask:0xf
	v_cndmask_b32_e32 v160, v168, v222, vcc
	v_cndmask_b32_e32 v161, v169, v223, vcc
	v_cndmask_b32_e32 v162, v220, v170, vcc
	v_cndmask_b32_e32 v163, v221, v171, vcc
	global_store_dwordx4 v210, v[160:163], s[8:9] offset:3072
	s_nop 1
	s_mov_b32 s2, s3
	s_mov_b32 s3, s101
	s_xor_b32 s100, s100, 0x100
	s_cmpk_lt_i32 s2, 0x2400
	s_cbranch_scc0 .Lnrm_p1_exit
	s_cmpk_lt_i32 s3, 0x2400
	s_cbranch_scc1 .Lnrm_p1_w16
	s_waitcnt vmcnt(8)
	s_branch .Lnrm_p1_top

.LBB0_1322:
	v_lshrrev_b32_e32 v210, 5, v176
	v_lshlrev_b32_e32 v210, 4, v210
	v_and_b32_e32 v211, 16, v176
	v_lshlrev_b32_e32 v211, 5, v211
	v_or_b32_e32 v210, v210, v211
	v_readlane_b32 s8, v254, 57
	v_readlane_b32 s9, v254, 58
	v_readlane_b32 s10, v253, 11
	v_readlane_b32 s11, v253, 12
	s_cmp_lg_u64 s[8:9], 0
	s_cselect_b32 s12, 1, 0
	s_cselect_b32 s10, s10, 0
	s_cselect_b32 s11, s11, 0
	s_mov_b32 s13, 0
	v_writelane_b32 v255, s13, 10
	v_writelane_b32 v255, s13, 11
	v_writelane_b32 v255, s10, 12
	v_writelane_b32 v255, s11, 13
	s_cmp_lg_u64 s[78:79], 0
	s_cselect_b32 s13, 1, 0
	v_readfirstlane_b32 s8, v32
	v_readfirstlane_b32 s9, v33
	v_readfirstlane_b32 s10, v36
	v_readfirstlane_b32 s11, v37
	v_writelane_b32 v255, s8, 14
	v_writelane_b32 v255, s9, 15
	v_writelane_b32 v255, s10, 16
	v_writelane_b32 v255, s11, 17
	v_writelane_b32 v255, s12, 18
	v_writelane_b32 v255, s13, 19
	v_readfirstlane_b32 s10, v38
	v_readfirstlane_b32 s11, v39
	s_add_u32 s10, s10, 0x1000
	s_addc_u32 s11, s11, 0
	global_load_dwordx4 v[178:181], v176, s[10:11] offset:-4096
	global_load_dwordx4 v[182:185], v176, s[10:11] offset:-3072
	global_load_dwordx4 v[186:189], v176, s[10:11] offset:-2048
	global_load_dwordx4 v[190:193], v176, s[10:11] offset:-1024
	global_load_dwordx4 v[194:197], v176, s[10:11] offset:0
	global_load_dwordx4 v[198:201], v176, s[10:11] offset:1024
	global_load_dwordx4 v[202:205], v176, s[10:11] offset:2048
	global_load_dwordx4 v[206:209], v176, s[10:11] offset:3072
	s_sub_i32 s3, s2, s88
